# wi 11/21 + S5 table inputs (lre lim bre bim cre cim) touched at table-function entry so later loads hit L2
# baseline (speedup 1.0000x reference)
.LBB0_10:
	s_or_b64 exec, exec, s[4:5]
	s_load_dwordx2 s[44:45], s[0:1], 0xf0
	v_and_b32_e32 v158, 63, v0
	s_waitcnt lgkmcnt(0)
	s_cmp_lt_i32 s44, 1
	s_cselect_b64 s[4:5], -1, 0
	s_cmp_gt_i32 s45, 0
	s_cselect_b64 s[6:7], -1, 0
	s_and_b64 s[4:5], s[4:5], s[6:7]
	s_andn2_b64 vcc, exec, s[4:5]
	s_cbranch_vccnz .LBB0_243
	s_cmpk_lt_i32 s2, 0x80
	s_cselect_b64 s[8:9], -1, 0
	s_cmpk_gt_i32 s2, 0x7f
	s_cselect_b64 s[6:7], -1, 0
	s_and_b64 vcc, exec, s[6:7]
	s_cbranch_vccnz .LBB0_87
	s_add_i32 s4, 0, 0x23098
	v_mov_b32_e32 v2, s4
	ds_read2_b64 v[2:5], v2 offset1:1
	s_ashr_i32 s10, s2, 2
	s_lshl_b32 s12, s10, 6
	s_ashr_i32 s13, s12, 31
	s_lshl_b64 s[4:5], s[12:13], 2
	s_waitcnt lgkmcnt(0)
	v_readfirstlane_b32 s14, v2
	v_readfirstlane_b32 s15, v3
	s_add_u32 s18, s14, s4
	s_addc_u32 s19, s15, s5
	v_readfirstlane_b32 s16, v4
	v_readfirstlane_b32 s17, v5
	s_add_u32 s20, s16, s4
	s_addc_u32 s21, s17, s5
	s_add_i32 s4, 0, 0x230a8
	v_mov_b32_e32 v2, s4
	ds_read_b64 v[2:3], v2
	s_ashr_i32 s11, s10, 31
	s_lshl_b64 s[4:5], s[10:11], 2
	v_mov_b32_e32 v4, 0
	s_mov_b32 s24, 0xfefa39ef
	s_waitcnt lgkmcnt(0)
	v_readfirstlane_b32 s22, v2
	v_readfirstlane_b32 s23, v3
	s_add_u32 s4, s22, s4
	s_addc_u32 s5, s23, s5
	global_load_dword v5, v4, s[4:5]
	s_add_i32 s50, 0, 0x230b0
	v_mov_b32_e32 v100, s50
	ds_read2_b64 v[100:103], v100 offset1:1
	s_add_i32 s50, 0, 0x230c0
	v_mov_b32_e32 v104, s50
	ds_read2_b64 v[104:107], v104 offset1:1
	s_lshl_b32 s60, s10, 12
	v_lshlrev_b32_e32 v108, 3, v0
	v_lshlrev_b32_e32 v109, 2, v158
	global_load_dword v110, v109, s[18:19]
	global_load_dword v111, v109, s[20:21]
	s_waitcnt lgkmcnt(0)
	v_readfirstlane_b32 s50, v100
	v_readfirstlane_b32 s51, v101
	v_readfirstlane_b32 s52, v102
	v_readfirstlane_b32 s53, v103
	v_readfirstlane_b32 s54, v104
	v_readfirstlane_b32 s55, v105
	v_readfirstlane_b32 s56, v106
	v_readfirstlane_b32 s57, v107
	s_add_u32 s50, s50, s60
	s_addc_u32 s51, s51, 0
	s_add_u32 s52, s52, s60
	s_addc_u32 s53, s53, 0
	s_add_u32 s54, s54, s60
	s_addc_u32 s55, s55, 0
	s_add_u32 s56, s56, s60
	s_addc_u32 s57, s57, 0
	global_load_dword v100, v108, s[50:51]
	global_load_dword v101, v108, s[52:53]
	global_load_dword v102, v108, s[54:55]
	global_load_dword v103, v108, s[56:57]
	s_mov_b32 s22, 0x652b82fe
	s_mov_b32 s23, 0x3ff71547
	s_mov_b32 s25, 0xbfe62e42
	s_mov_b32 s26, 0x3b39803f
	s_mov_b32 s27, 0xbc7abc9e
	v_mov_b32_e32 v6, 0xfca7ab0c
	v_mov_b32_e32 v7, 0x3e928af3
	s_mov_b32 s28, 0x6a5dcb37
	s_mov_b32 s29, 0x3e5ade15
	v_mov_b32_e32 v8, 0x623fde64
	v_mov_b32_e32 v9, 0x3ec71dee
	v_mov_b64_e32 v[2:3], v[6:7]
	v_mov_b32_e32 v10, 0x7c89e6b0
	v_mov_b32_e32 v11, 0x3efa0199
	v_mov_b64_e32 v[24:25], v[8:9]
	v_mov_b32_e32 v12, 0x14761f6e
	v_mov_b32_e32 v13, 0x3f2a01a0
	v_mov_b64_e32 v[26:27], v[10:11]
	v_mov_b32_e32 v14, 0x1852b7b0
	v_mov_b32_e32 v15, 0x3f56c16c
	v_mov_b64_e32 v[28:29], v[12:13]
	v_mov_b32_e32 v16, 0x11122322
	v_mov_b32_e32 v17, 0x3f811111
	v_mov_b64_e32 v[30:31], v[14:15]
	v_mov_b32_e32 v18, 0x555502a1
	v_mov_b32_e32 v19, 0x3fa55555
	v_mov_b64_e32 v[32:33], v[16:17]
	v_mov_b32_e32 v20, 0x55555511
	v_mov_b32_e32 v21, 0x3fc55555
	v_mov_b64_e32 v[34:35], v[18:19]
	v_mov_b32_e32 v22, 11
	v_mov_b32_e32 v23, 0x3fe00000
	v_mov_b64_e32 v[36:37], v[20:21]
	v_mov_b64_e32 v[38:39], v[22:23]
	s_mov_b32 s4, 0x44800000
	s_mov_b32 s5, 0xc4866000
	v_mov_b32_e32 v50, 0x7ff00000
	v_lshlrev_b32_e32 v51, 3, v0
	s_mov_b32 s34, 0
	s_mov_b32 s50, 0
	s_mov_b32 s52, 0
	s_mov_b32 s56, 0x54442d18
	s_mov_b32 s62, 0x6dc9c883
	s_mov_b32 s64, 0x33145c00
	s_mov_b32 s66, 0x252049c0
	s_mov_b32 s68, 0xeb1c432d
	s_mov_b32 s70, 0
	s_mov_b32 s72, 0
	s_mov_b32 s74, 0x46cc5e42
	s_mov_b32 s76, 0x55555555
	s_mov_b32 s78, 0xf9a43bb8
	s_mov_b64 s[30:31], 0
	s_mov_b32 s41, 0xf0f1
	s_mov_b32 s35, 0x41d00000
	s_mov_b32 s51, 0x7b000000
	s_movk_i32 s82, 0xff80
	s_mov_b32 s53, 0x7ff00000
	s_mov_b32 s55, 0x3ff921fb
	s_mov_b32 s57, 0xbff921fb
	s_mov_b32 s59, 0x3c91a626
	s_mov_b32 s60, 0x33145c07
	s_mov_b32 s63, 0x3fe45f30
	s_mov_b32 s65, 0xbc91a626
	s_mov_b32 s67, 0xb97b839a
	s_mov_b32 s69, 0xbf1a36e2
	s_mov_b32 s71, 0x40900000
	s_mov_b32 s73, 0xc090cc00
	s_mov_b32 s75, 0xbda907db
	s_mov_b32 s77, 0xbfc55555
	s_mov_b32 s79, 0x3de5e0b2
	v_add_u32_e32 v52, 0, v51
	s_brev_b32 s83, 1
	s_movk_i32 s84, 0x1f8
	s_movk_i32 s85, 0x23f
	v_mov_b32_e32 v53, 0x40100000
	v_mov_b32_e32 v54, 0x3ff00000
	v_mov_b32_e32 v55, 0x7ff80000
	v_mov_b32_e32 v56, v0
	s_waitcnt vmcnt(0)
	v_cvt_f64_f32_e32 v[40:41], v5
	v_mul_f64 v[42:43], v[40:41], s[22:23]
	v_rndne_f64_e32 v[42:43], v[42:43]
	v_fmac_f64_e32 v[40:41], s[24:25], v[42:43]
	v_fmac_f64_e32 v[40:41], s[26:27], v[42:43]
	v_fmac_f64_e32 v[2:3], s[28:29], v[40:41]
	v_fmac_f64_e32 v[24:25], v[40:41], v[2:3]
	v_fmac_f64_e32 v[26:27], v[40:41], v[24:25]
	v_fmac_f64_e32 v[28:29], v[40:41], v[26:27]
	v_fmac_f64_e32 v[30:31], v[40:41], v[28:29]
	v_fmac_f64_e32 v[32:33], v[40:41], v[30:31]
	v_fmac_f64_e32 v[34:35], v[40:41], v[32:33]
	v_fmac_f64_e32 v[36:37], v[40:41], v[34:35]
	v_fmac_f64_e32 v[38:39], v[40:41], v[36:37]
	v_fma_f64 v[2:3], v[40:41], v[38:39], 1.0
	v_cvt_i32_f64_e32 v44, v[42:43]
	v_fma_f64 v[2:3], v[40:41], v[2:3], 1.0
	v_ldexp_f64 v[2:3], v[2:3], v44
	v_cmp_nlt_f32_e32 vcc, s4, v5
	v_cmp_ngt_f32_e64 s[4:5], s5, v5
	v_mov_b32_e32 v24, 0x9037ab78
	v_cndmask_b32_e32 v3, v50, v3, vcc
	s_and_b64 vcc, s[4:5], vcc
	v_cndmask_b32_e64 v3, 0, v3, s[4:5]
	v_cndmask_b32_e32 v2, 0, v2, vcc
	v_mov_b32_e32 v25, 0x3e21eeb6
	v_mov_b32_e32 v26, 0xa17f65f6
	v_mov_b32_e32 v27, 0xbe927e4f
	v_mov_b32_e32 v28, 0x19f4ec90
	v_mov_b32_e32 v29, 0x3efa01a0
	v_mov_b32_e32 v30, 0x16c16967
	v_mov_b32_e32 v31, 0xbf56c16c
	v_mov_b32_e32 v32, 0x55555555
	v_mov_b32_e32 v34, 0xb42fdfa7
	v_mov_b32_e32 v35, 0xbe5ae600
	v_mov_b32_e32 v36, 0x796cde01
	v_mov_b32_e32 v37, 0x3ec71de3
	v_mov_b32_e32 v38, 0x19e83e5c
	v_mov_b32_e32 v39, 0xbf2a01a0
	v_mov_b32_e32 v40, 0x11110bb3
	s_branch .LBB0_14
